# zred: scanner forms y'=d2+c1*d1 per lane before the cross-lane sum and reduces four steps' y' together (transpose-reduce: 11 ops per 4 steps instead of 16 DPP adds), one ds_write_b32 per 4 steps
# baseline (speedup 1.0000x reference)
.LBB0_726:
	s_and_b32 s1, s0, 1
	s_lshl_b32 s31, s1, 8
	s_mul_i32 s30, s1, 0xa000
	s_add_i32 s31, s31, 0x18000
	v_add_u32_e32 v6, s30, v151
	v_mov_b32_e32 v8, s31
	v_lshl_add_u32 v7, s1, 13, v0
	v_lshl_add_u32 v9, s1, 11, v39
	v_add_u32_e32 v22, 0x400, v9
	s_mov_b32 s98, 0xaaaaaaaa
	s_mov_b32 s99, 0xaaaaaaaa
	s_mov_b32 s100, 0xcccccccc
	s_mov_b32 s101, 0xcccccccc
	v_and_b32_e32 v56, 3, v170
	v_lshl_add_u32 v56, v56, 6, v9
	ds_read_b128 v[58:61], v6
	ds_read_b128 v[62:65], v6 offset:16
	ds_read_b128 v[66:69], v6 offset:32
	ds_read_b128 v[70:73], v6 offset:48
	ds_read_b128 v[74:77], v6 offset:64
	ds_read2st64_b32 v[118:119], v7 offset1:1
	ds_read_b128 v[120:123], v8
	ds_read_b128 v[78:81], v6 offset:1280
	ds_read_b128 v[82:85], v6 offset:1296
	ds_read_b128 v[86:89], v6 offset:1312
	ds_read_b128 v[90:93], v6 offset:1328
	ds_read_b128 v[94:97], v6 offset:1344
	ds_read_b128 v[98:101], v6 offset:2560
	ds_read_b128 v[102:105], v6 offset:2576
	ds_read_b128 v[106:109], v6 offset:2592
	ds_read_b128 v[110:113], v6 offset:2608
	ds_read_b128 v[114:117], v6 offset:2624
	ds_read2st64_b32 v[206:207], v7 offset0:2 offset1:3
	ds_read_b128 v[208:211], v8 offset:16
	s_waitcnt lgkmcnt(12)
	v_pk_mul_f32 v[10:11], v[2:3], v[58:59] op_sel_hi:[0,1]
	v_pk_fma_f32 v[10:11], v[2:3], v[60:61], v[10:11] op_sel:[1,0,0] op_sel_hi:[1,1,1]
	v_pk_fma_f32 v[10:11], v[4:5], v[62:63], v[10:11] op_sel_hi:[0,1,1]
	v_pk_fma_f32 v[10:11], v[4:5], v[64:65], v[10:11] op_sel:[1,0,0] op_sel_hi:[1,1,1]
	v_fma_f32 v24, v120, v10, v11
	v_pk_mul_f32 v[18:19], v[74:75], v[118:119] op_sel_hi:[1,0]
	v_add_f32_dpp v10, v10, v10 quad_perm:[1,0,3,2] row_mask:0xf bank_mask:0xf bound_ctrl:1
	v_pk_mul_f32 v[20:21], v[76:77], v[118:119] op_sel_hi:[1,0]
	v_pk_fma_f32 v[18:19], v[2:3], v[66:67], v[18:19]
	v_add_f32_dpp v10, v10, v10 quad_perm:[2,3,0,1] row_mask:0xf bank_mask:0xf bound_ctrl:1
	v_pk_fma_f32 v[20:21], v[4:5], v[68:69], v[20:21]
	s_nop 0
	v_add_f32_dpp v10, v10, v10 row_half_mirror row_mask:0xf bank_mask:0xf bound_ctrl:1
	s_nop 0
	s_nop 0
	v_add_f32_dpp v10, v10, v10 row_mirror row_mask:0xf bank_mask:0xf bound_ctrl:1
	v_pk_fma_f32 v[2:3], v[70:71], v[10:11], v[18:19] op_sel_hi:[1,0,1]
	v_pk_fma_f32 v[4:5], v[72:73], v[10:11], v[20:21] op_sel_hi:[1,0,1]
	ds_read_b128 v[186:189], v6 offset:3840
	ds_read_b128 v[190:193], v6 offset:3856
	ds_read_b128 v[194:197], v6 offset:3872
	ds_read_b128 v[198:201], v6 offset:3888
	ds_read_b128 v[202:205], v6 offset:3904
	s_waitcnt lgkmcnt(12)
	v_pk_mul_f32 v[12:13], v[2:3], v[78:79] op_sel_hi:[0,1]
	v_pk_fma_f32 v[12:13], v[2:3], v[80:81], v[12:13] op_sel:[1,0,0] op_sel_hi:[1,1,1]
	v_pk_fma_f32 v[12:13], v[4:5], v[82:83], v[12:13] op_sel_hi:[0,1,1]
	v_pk_fma_f32 v[12:13], v[4:5], v[84:85], v[12:13] op_sel:[1,0,0] op_sel_hi:[1,1,1]
	v_fma_f32 v25, v122, v12, v13
	v_pk_mul_f32 v[18:19], v[94:95], v[118:119] op_sel:[0,1] op_sel_hi:[1,1]
	v_add_f32_dpp v12, v12, v12 quad_perm:[1,0,3,2] row_mask:0xf bank_mask:0xf bound_ctrl:1
	v_pk_mul_f32 v[20:21], v[96:97], v[118:119] op_sel:[0,1] op_sel_hi:[1,1]
	v_pk_fma_f32 v[18:19], v[2:3], v[86:87], v[18:19]
	v_add_f32_dpp v12, v12, v12 quad_perm:[2,3,0,1] row_mask:0xf bank_mask:0xf bound_ctrl:1
	v_pk_fma_f32 v[20:21], v[4:5], v[88:89], v[20:21]
	s_nop 0
	v_add_f32_dpp v12, v12, v12 row_half_mirror row_mask:0xf bank_mask:0xf bound_ctrl:1
	s_nop 0
	s_nop 0
	v_add_f32_dpp v12, v12, v12 row_mirror row_mask:0xf bank_mask:0xf bound_ctrl:1
	v_pk_fma_f32 v[2:3], v[90:91], v[12:13], v[18:19] op_sel_hi:[1,0,1]
	v_pk_fma_f32 v[4:5], v[92:93], v[12:13], v[20:21] op_sel_hi:[1,0,1]
	ds_read_b128 v[58:61], v6 offset:5120
	ds_read_b128 v[62:65], v6 offset:5136
	ds_read_b128 v[66:69], v6 offset:5152
	ds_read_b128 v[70:73], v6 offset:5168
	ds_read_b128 v[74:77], v6 offset:5184
	ds_read2st64_b32 v[118:119], v7 offset0:4 offset1:5
	ds_read_b128 v[120:123], v8 offset:32
	s_waitcnt lgkmcnt(12)
	v_pk_mul_f32 v[14:15], v[2:3], v[98:99] op_sel_hi:[0,1]
	v_pk_fma_f32 v[14:15], v[2:3], v[100:101], v[14:15] op_sel:[1,0,0] op_sel_hi:[1,1,1]
	v_pk_fma_f32 v[14:15], v[4:5], v[102:103], v[14:15] op_sel_hi:[0,1,1]
	v_pk_fma_f32 v[14:15], v[4:5], v[104:105], v[14:15] op_sel:[1,0,0] op_sel_hi:[1,1,1]
	v_fma_f32 v26, v208, v14, v15
	v_pk_mul_f32 v[18:19], v[114:115], v[206:207] op_sel_hi:[1,0]
	v_add_f32_dpp v14, v14, v14 quad_perm:[1,0,3,2] row_mask:0xf bank_mask:0xf bound_ctrl:1
	v_pk_mul_f32 v[20:21], v[116:117], v[206:207] op_sel_hi:[1,0]
	v_pk_fma_f32 v[18:19], v[2:3], v[106:107], v[18:19]
	v_add_f32_dpp v14, v14, v14 quad_perm:[2,3,0,1] row_mask:0xf bank_mask:0xf bound_ctrl:1
	v_pk_fma_f32 v[20:21], v[4:5], v[108:109], v[20:21]
	s_nop 0
	v_add_f32_dpp v14, v14, v14 row_half_mirror row_mask:0xf bank_mask:0xf bound_ctrl:1
	s_nop 0
	s_nop 0
	v_add_f32_dpp v14, v14, v14 row_mirror row_mask:0xf bank_mask:0xf bound_ctrl:1
	v_pk_fma_f32 v[2:3], v[110:111], v[14:15], v[18:19] op_sel_hi:[1,0,1]
	v_pk_fma_f32 v[4:5], v[112:113], v[14:15], v[20:21] op_sel_hi:[1,0,1]
	ds_read_b128 v[78:81], v6 offset:6400
	ds_read_b128 v[82:85], v6 offset:6416
	ds_read_b128 v[86:89], v6 offset:6432
	ds_read_b128 v[90:93], v6 offset:6448
	ds_read_b128 v[94:97], v6 offset:6464
	s_waitcnt lgkmcnt(12)
	v_pk_mul_f32 v[16:17], v[2:3], v[186:187] op_sel_hi:[0,1]
	v_pk_fma_f32 v[16:17], v[2:3], v[188:189], v[16:17] op_sel:[1,0,0] op_sel_hi:[1,1,1]
	v_pk_fma_f32 v[16:17], v[4:5], v[190:191], v[16:17] op_sel_hi:[0,1,1]
	v_pk_fma_f32 v[16:17], v[4:5], v[192:193], v[16:17] op_sel:[1,0,0] op_sel_hi:[1,1,1]
	v_fma_f32 v27, v210, v16, v17
	v_pk_mul_f32 v[18:19], v[202:203], v[206:207] op_sel:[0,1] op_sel_hi:[1,1]
	v_add_f32_dpp v16, v16, v16 quad_perm:[1,0,3,2] row_mask:0xf bank_mask:0xf bound_ctrl:1
	v_pk_mul_f32 v[20:21], v[204:205], v[206:207] op_sel:[0,1] op_sel_hi:[1,1]
	v_pk_fma_f32 v[18:19], v[2:3], v[194:195], v[18:19]
	v_add_f32_dpp v16, v16, v16 quad_perm:[2,3,0,1] row_mask:0xf bank_mask:0xf bound_ctrl:1
	v_pk_fma_f32 v[20:21], v[4:5], v[196:197], v[20:21]
	s_nop 0
	v_add_f32_dpp v16, v16, v16 row_half_mirror row_mask:0xf bank_mask:0xf bound_ctrl:1
	s_nop 0
	s_nop 0
	v_add_f32_dpp v16, v16, v16 row_mirror row_mask:0xf bank_mask:0xf bound_ctrl:1
	v_pk_fma_f32 v[2:3], v[198:199], v[16:17], v[18:19] op_sel_hi:[1,0,1]
	v_pk_fma_f32 v[4:5], v[200:201], v[16:17], v[20:21] op_sel_hi:[1,0,1]
	ds_read_b128 v[98:101], v6 offset:7680
	ds_read_b128 v[102:105], v6 offset:7696
	ds_read_b128 v[106:109], v6 offset:7712
	ds_read_b128 v[110:113], v6 offset:7728
	ds_read_b128 v[114:117], v6 offset:7744
	ds_read2st64_b32 v[206:207], v7 offset0:6 offset1:7
	ds_read_b128 v[208:211], v8 offset:48
	s_waitcnt lgkmcnt(12)
	v_pk_mul_f32 v[10:11], v[2:3], v[58:59] op_sel_hi:[0,1]
	v_pk_fma_f32 v[10:11], v[2:3], v[60:61], v[10:11] op_sel:[1,0,0] op_sel_hi:[1,1,1]
	v_pk_fma_f32 v[10:11], v[4:5], v[62:63], v[10:11] op_sel_hi:[0,1,1]
	v_pk_fma_f32 v[10:11], v[4:5], v[64:65], v[10:11] op_sel:[1,0,0] op_sel_hi:[1,1,1]
	v_fma_f32 v28, v120, v10, v11
	v_pk_mul_f32 v[18:19], v[74:75], v[118:119] op_sel_hi:[1,0]
	v_add_f32_dpp v10, v10, v10 quad_perm:[1,0,3,2] row_mask:0xf bank_mask:0xf bound_ctrl:1
	v_pk_mul_f32 v[20:21], v[76:77], v[118:119] op_sel_hi:[1,0]
	v_pk_fma_f32 v[18:19], v[2:3], v[66:67], v[18:19]
	v_add_f32_dpp v10, v10, v10 quad_perm:[2,3,0,1] row_mask:0xf bank_mask:0xf bound_ctrl:1
	v_pk_fma_f32 v[20:21], v[4:5], v[68:69], v[20:21]
	v_cndmask_b32_e64 v32, v24, v25, s[98:99]
	v_add_f32_dpp v10, v10, v10 row_half_mirror row_mask:0xf bank_mask:0xf bound_ctrl:1
	v_cndmask_b32_e64 v33, v25, v24, s[98:99]
	v_cndmask_b32_e64 v23, v26, v27, s[98:99]
	v_add_f32_dpp v10, v10, v10 row_mirror row_mask:0xf bank_mask:0xf bound_ctrl:1
	v_pk_fma_f32 v[2:3], v[70:71], v[10:11], v[18:19] op_sel_hi:[1,0,1]
	v_pk_fma_f32 v[4:5], v[72:73], v[10:11], v[20:21] op_sel_hi:[1,0,1]
	ds_read_b128 v[186:189], v6 offset:8960
	ds_read_b128 v[190:193], v6 offset:8976
	ds_read_b128 v[194:197], v6 offset:8992
	ds_read_b128 v[198:201], v6 offset:9008
	ds_read_b128 v[202:205], v6 offset:9024
	s_waitcnt lgkmcnt(12)
	v_pk_mul_f32 v[12:13], v[2:3], v[78:79] op_sel_hi:[0,1]
	v_pk_fma_f32 v[12:13], v[2:3], v[80:81], v[12:13] op_sel:[1,0,0] op_sel_hi:[1,1,1]
	v_pk_fma_f32 v[12:13], v[4:5], v[82:83], v[12:13] op_sel_hi:[0,1,1]
	v_pk_fma_f32 v[12:13], v[4:5], v[84:85], v[12:13] op_sel:[1,0,0] op_sel_hi:[1,1,1]
	v_fma_f32 v29, v122, v12, v13
	v_pk_mul_f32 v[18:19], v[94:95], v[118:119] op_sel:[0,1] op_sel_hi:[1,1]
	v_add_f32_dpp v12, v12, v12 quad_perm:[1,0,3,2] row_mask:0xf bank_mask:0xf bound_ctrl:1
	v_pk_mul_f32 v[20:21], v[96:97], v[118:119] op_sel:[0,1] op_sel_hi:[1,1]
	v_pk_fma_f32 v[18:19], v[2:3], v[86:87], v[18:19]
	v_add_f32_dpp v12, v12, v12 quad_perm:[2,3,0,1] row_mask:0xf bank_mask:0xf bound_ctrl:1
	v_pk_fma_f32 v[20:21], v[4:5], v[88:89], v[20:21]
	v_cndmask_b32_e64 v57, v27, v26, s[98:99]
	v_add_f32_dpp v12, v12, v12 row_half_mirror row_mask:0xf bank_mask:0xf bound_ctrl:1
	v_add_f32_dpp v32, v33, v32 quad_perm:[1,0,3,2] row_mask:0xf bank_mask:0xf bound_ctrl:1
	v_add_f32_dpp v23, v57, v23 quad_perm:[1,0,3,2] row_mask:0xf bank_mask:0xf bound_ctrl:1
	v_add_f32_dpp v12, v12, v12 row_mirror row_mask:0xf bank_mask:0xf bound_ctrl:1
	v_pk_fma_f32 v[2:3], v[90:91], v[12:13], v[18:19] op_sel_hi:[1,0,1]
	v_pk_fma_f32 v[4:5], v[92:93], v[12:13], v[20:21] op_sel_hi:[1,0,1]
	ds_read_b128 v[58:61], v6 offset:10240
	ds_read_b128 v[62:65], v6 offset:10256
	ds_read_b128 v[66:69], v6 offset:10272
	ds_read_b128 v[70:73], v6 offset:10288
	ds_read_b128 v[74:77], v6 offset:10304
	ds_read2st64_b32 v[118:119], v7 offset0:8 offset1:9
	ds_read_b128 v[120:123], v8 offset:64
	s_waitcnt lgkmcnt(12)
	v_pk_mul_f32 v[14:15], v[2:3], v[98:99] op_sel_hi:[0,1]
	v_pk_fma_f32 v[14:15], v[2:3], v[100:101], v[14:15] op_sel:[1,0,0] op_sel_hi:[1,1,1]
	v_pk_fma_f32 v[14:15], v[4:5], v[102:103], v[14:15] op_sel_hi:[0,1,1]
	v_pk_fma_f32 v[14:15], v[4:5], v[104:105], v[14:15] op_sel:[1,0,0] op_sel_hi:[1,1,1]
	v_fma_f32 v30, v208, v14, v15
	v_pk_mul_f32 v[18:19], v[114:115], v[206:207] op_sel_hi:[1,0]
	v_add_f32_dpp v14, v14, v14 quad_perm:[1,0,3,2] row_mask:0xf bank_mask:0xf bound_ctrl:1
	v_pk_mul_f32 v[20:21], v[116:117], v[206:207] op_sel_hi:[1,0]
	v_pk_fma_f32 v[18:19], v[2:3], v[106:107], v[18:19]
	v_add_f32_dpp v14, v14, v14 quad_perm:[2,3,0,1] row_mask:0xf bank_mask:0xf bound_ctrl:1
	v_pk_fma_f32 v[20:21], v[4:5], v[108:109], v[20:21]
	v_cndmask_b32_e64 v57, v23, v32, s[100:101]
	v_add_f32_dpp v14, v14, v14 row_half_mirror row_mask:0xf bank_mask:0xf bound_ctrl:1
	v_cndmask_b32_e64 v33, v32, v23, s[100:101]
	v_add_f32_dpp v33, v57, v33 quad_perm:[2,3,0,1] row_mask:0xf bank_mask:0xf bound_ctrl:1
	v_add_f32_dpp v14, v14, v14 row_mirror row_mask:0xf bank_mask:0xf bound_ctrl:1
	v_pk_fma_f32 v[2:3], v[110:111], v[14:15], v[18:19] op_sel_hi:[1,0,1]
	v_pk_fma_f32 v[4:5], v[112:113], v[14:15], v[20:21] op_sel_hi:[1,0,1]
	ds_read_b128 v[78:81], v6 offset:11520
	ds_read_b128 v[82:85], v6 offset:11536
	ds_read_b128 v[86:89], v6 offset:11552
	ds_read_b128 v[90:93], v6 offset:11568
	ds_read_b128 v[94:97], v6 offset:11584
	s_waitcnt lgkmcnt(12)
	v_pk_mul_f32 v[16:17], v[2:3], v[186:187] op_sel_hi:[0,1]
	v_pk_fma_f32 v[16:17], v[2:3], v[188:189], v[16:17] op_sel:[1,0,0] op_sel_hi:[1,1,1]
	v_pk_fma_f32 v[16:17], v[4:5], v[190:191], v[16:17] op_sel_hi:[0,1,1]
	v_pk_fma_f32 v[16:17], v[4:5], v[192:193], v[16:17] op_sel:[1,0,0] op_sel_hi:[1,1,1]
	v_fma_f32 v31, v210, v16, v17
	v_pk_mul_f32 v[18:19], v[202:203], v[206:207] op_sel:[0,1] op_sel_hi:[1,1]
	v_add_f32_dpp v16, v16, v16 quad_perm:[1,0,3,2] row_mask:0xf bank_mask:0xf bound_ctrl:1
	v_pk_mul_f32 v[20:21], v[204:205], v[206:207] op_sel:[0,1] op_sel_hi:[1,1]
	v_pk_fma_f32 v[18:19], v[2:3], v[194:195], v[18:19]
	v_add_f32_dpp v16, v16, v16 quad_perm:[2,3,0,1] row_mask:0xf bank_mask:0xf bound_ctrl:1
	v_pk_fma_f32 v[20:21], v[4:5], v[196:197], v[20:21]
	v_add_f32_dpp v33, v33, v33 row_ror:4 row_mask:0xf bank_mask:0xf bound_ctrl:1
	v_add_f32_dpp v16, v16, v16 row_half_mirror row_mask:0xf bank_mask:0xf bound_ctrl:1
	s_nop 0
	v_add_f32_dpp v33, v33, v33 row_ror:8 row_mask:0xf bank_mask:0xf bound_ctrl:1
	v_add_f32_dpp v16, v16, v16 row_mirror row_mask:0xf bank_mask:0xf bound_ctrl:1
	v_pk_fma_f32 v[2:3], v[198:199], v[16:17], v[18:19] op_sel_hi:[1,0,1]
	v_pk_fma_f32 v[4:5], v[200:201], v[16:17], v[20:21] op_sel_hi:[1,0,1]
	ds_write_b32 v56, v33
	ds_read_b128 v[98:101], v6 offset:12800
	ds_read_b128 v[102:105], v6 offset:12816
	ds_read_b128 v[106:109], v6 offset:12832
	ds_read_b128 v[110:113], v6 offset:12848
	ds_read_b128 v[114:117], v6 offset:12864
	ds_read2st64_b32 v[206:207], v7 offset0:10 offset1:11
	ds_read_b128 v[208:211], v8 offset:80
	s_waitcnt lgkmcnt(13)
	v_pk_mul_f32 v[10:11], v[2:3], v[58:59] op_sel_hi:[0,1]
	v_pk_fma_f32 v[10:11], v[2:3], v[60:61], v[10:11] op_sel:[1,0,0] op_sel_hi:[1,1,1]
	v_pk_fma_f32 v[10:11], v[4:5], v[62:63], v[10:11] op_sel_hi:[0,1,1]
	v_pk_fma_f32 v[10:11], v[4:5], v[64:65], v[10:11] op_sel:[1,0,0] op_sel_hi:[1,1,1]
	v_fma_f32 v24, v120, v10, v11
	v_pk_mul_f32 v[18:19], v[74:75], v[118:119] op_sel_hi:[1,0]
	v_add_f32_dpp v10, v10, v10 quad_perm:[1,0,3,2] row_mask:0xf bank_mask:0xf bound_ctrl:1
	v_pk_mul_f32 v[20:21], v[76:77], v[118:119] op_sel_hi:[1,0]
	v_pk_fma_f32 v[18:19], v[2:3], v[66:67], v[18:19]
	v_add_f32_dpp v10, v10, v10 quad_perm:[2,3,0,1] row_mask:0xf bank_mask:0xf bound_ctrl:1
	v_pk_fma_f32 v[20:21], v[4:5], v[68:69], v[20:21]
	v_cndmask_b32_e64 v32, v28, v29, s[98:99]
	v_add_f32_dpp v10, v10, v10 row_half_mirror row_mask:0xf bank_mask:0xf bound_ctrl:1
	v_cndmask_b32_e64 v33, v29, v28, s[98:99]
	v_cndmask_b32_e64 v23, v30, v31, s[98:99]
	v_add_f32_dpp v10, v10, v10 row_mirror row_mask:0xf bank_mask:0xf bound_ctrl:1
	v_pk_fma_f32 v[2:3], v[70:71], v[10:11], v[18:19] op_sel_hi:[1,0,1]
	v_pk_fma_f32 v[4:5], v[72:73], v[10:11], v[20:21] op_sel_hi:[1,0,1]
	ds_read_b128 v[186:189], v6 offset:14080
	ds_read_b128 v[190:193], v6 offset:14096
	ds_read_b128 v[194:197], v6 offset:14112
	ds_read_b128 v[198:201], v6 offset:14128
	ds_read_b128 v[202:205], v6 offset:14144
	s_waitcnt lgkmcnt(13)
	v_pk_mul_f32 v[12:13], v[2:3], v[78:79] op_sel_hi:[0,1]
	v_pk_fma_f32 v[12:13], v[2:3], v[80:81], v[12:13] op_sel:[1,0,0] op_sel_hi:[1,1,1]
	v_pk_fma_f32 v[12:13], v[4:5], v[82:83], v[12:13] op_sel_hi:[0,1,1]
	v_pk_fma_f32 v[12:13], v[4:5], v[84:85], v[12:13] op_sel:[1,0,0] op_sel_hi:[1,1,1]
	v_fma_f32 v25, v122, v12, v13
	v_pk_mul_f32 v[18:19], v[94:95], v[118:119] op_sel:[0,1] op_sel_hi:[1,1]
	v_add_f32_dpp v12, v12, v12 quad_perm:[1,0,3,2] row_mask:0xf bank_mask:0xf bound_ctrl:1
	v_pk_mul_f32 v[20:21], v[96:97], v[118:119] op_sel:[0,1] op_sel_hi:[1,1]
	v_pk_fma_f32 v[18:19], v[2:3], v[86:87], v[18:19]
	v_add_f32_dpp v12, v12, v12 quad_perm:[2,3,0,1] row_mask:0xf bank_mask:0xf bound_ctrl:1
	v_pk_fma_f32 v[20:21], v[4:5], v[88:89], v[20:21]
	v_cndmask_b32_e64 v57, v31, v30, s[98:99]
	v_add_f32_dpp v12, v12, v12 row_half_mirror row_mask:0xf bank_mask:0xf bound_ctrl:1
	v_add_f32_dpp v32, v33, v32 quad_perm:[1,0,3,2] row_mask:0xf bank_mask:0xf bound_ctrl:1
	v_add_f32_dpp v23, v57, v23 quad_perm:[1,0,3,2] row_mask:0xf bank_mask:0xf bound_ctrl:1
	v_add_f32_dpp v12, v12, v12 row_mirror row_mask:0xf bank_mask:0xf bound_ctrl:1
	v_pk_fma_f32 v[2:3], v[90:91], v[12:13], v[18:19] op_sel_hi:[1,0,1]
	v_pk_fma_f32 v[4:5], v[92:93], v[12:13], v[20:21] op_sel_hi:[1,0,1]
	ds_read_b128 v[58:61], v6 offset:15360
	ds_read_b128 v[62:65], v6 offset:15376
	ds_read_b128 v[66:69], v6 offset:15392
	ds_read_b128 v[70:73], v6 offset:15408
	ds_read_b128 v[74:77], v6 offset:15424
	ds_read2st64_b32 v[118:119], v7 offset0:12 offset1:13
	ds_read_b128 v[120:123], v8 offset:96
	s_waitcnt lgkmcnt(12)
	v_pk_mul_f32 v[14:15], v[2:3], v[98:99] op_sel_hi:[0,1]
	v_pk_fma_f32 v[14:15], v[2:3], v[100:101], v[14:15] op_sel:[1,0,0] op_sel_hi:[1,1,1]
	v_pk_fma_f32 v[14:15], v[4:5], v[102:103], v[14:15] op_sel_hi:[0,1,1]
	v_pk_fma_f32 v[14:15], v[4:5], v[104:105], v[14:15] op_sel:[1,0,0] op_sel_hi:[1,1,1]
	v_fma_f32 v26, v208, v14, v15
	v_pk_mul_f32 v[18:19], v[114:115], v[206:207] op_sel_hi:[1,0]
	v_add_f32_dpp v14, v14, v14 quad_perm:[1,0,3,2] row_mask:0xf bank_mask:0xf bound_ctrl:1
	v_pk_mul_f32 v[20:21], v[116:117], v[206:207] op_sel_hi:[1,0]
	v_pk_fma_f32 v[18:19], v[2:3], v[106:107], v[18:19]
	v_add_f32_dpp v14, v14, v14 quad_perm:[2,3,0,1] row_mask:0xf bank_mask:0xf bound_ctrl:1
	v_pk_fma_f32 v[20:21], v[4:5], v[108:109], v[20:21]
	v_cndmask_b32_e64 v57, v23, v32, s[100:101]
	v_add_f32_dpp v14, v14, v14 row_half_mirror row_mask:0xf bank_mask:0xf bound_ctrl:1
	v_cndmask_b32_e64 v33, v32, v23, s[100:101]
	v_add_f32_dpp v33, v57, v33 quad_perm:[2,3,0,1] row_mask:0xf bank_mask:0xf bound_ctrl:1
	v_add_f32_dpp v14, v14, v14 row_mirror row_mask:0xf bank_mask:0xf bound_ctrl:1
	v_pk_fma_f32 v[2:3], v[110:111], v[14:15], v[18:19] op_sel_hi:[1,0,1]
	v_pk_fma_f32 v[4:5], v[112:113], v[14:15], v[20:21] op_sel_hi:[1,0,1]
	ds_read_b128 v[78:81], v6 offset:16640
	ds_read_b128 v[82:85], v6 offset:16656
	ds_read_b128 v[86:89], v6 offset:16672
	ds_read_b128 v[90:93], v6 offset:16688
	ds_read_b128 v[94:97], v6 offset:16704
	s_waitcnt lgkmcnt(12)
	v_pk_mul_f32 v[16:17], v[2:3], v[186:187] op_sel_hi:[0,1]
	v_pk_fma_f32 v[16:17], v[2:3], v[188:189], v[16:17] op_sel:[1,0,0] op_sel_hi:[1,1,1]
	v_pk_fma_f32 v[16:17], v[4:5], v[190:191], v[16:17] op_sel_hi:[0,1,1]
	v_pk_fma_f32 v[16:17], v[4:5], v[192:193], v[16:17] op_sel:[1,0,0] op_sel_hi:[1,1,1]
	v_fma_f32 v27, v210, v16, v17
	v_pk_mul_f32 v[18:19], v[202:203], v[206:207] op_sel:[0,1] op_sel_hi:[1,1]
	v_add_f32_dpp v16, v16, v16 quad_perm:[1,0,3,2] row_mask:0xf bank_mask:0xf bound_ctrl:1
	v_pk_mul_f32 v[20:21], v[204:205], v[206:207] op_sel:[0,1] op_sel_hi:[1,1]
	v_pk_fma_f32 v[18:19], v[2:3], v[194:195], v[18:19]
	v_add_f32_dpp v16, v16, v16 quad_perm:[2,3,0,1] row_mask:0xf bank_mask:0xf bound_ctrl:1
	v_pk_fma_f32 v[20:21], v[4:5], v[196:197], v[20:21]
	v_add_f32_dpp v33, v33, v33 row_ror:4 row_mask:0xf bank_mask:0xf bound_ctrl:1
	v_add_f32_dpp v16, v16, v16 row_half_mirror row_mask:0xf bank_mask:0xf bound_ctrl:1
	s_nop 0
	v_add_f32_dpp v33, v33, v33 row_ror:8 row_mask:0xf bank_mask:0xf bound_ctrl:1
	v_add_f32_dpp v16, v16, v16 row_mirror row_mask:0xf bank_mask:0xf bound_ctrl:1
	v_pk_fma_f32 v[2:3], v[198:199], v[16:17], v[18:19] op_sel_hi:[1,0,1]
	v_pk_fma_f32 v[4:5], v[200:201], v[16:17], v[20:21] op_sel_hi:[1,0,1]
	ds_write_b32 v56, v33 offset:256
	ds_read_b128 v[98:101], v6 offset:17920
	ds_read_b128 v[102:105], v6 offset:17936
	ds_read_b128 v[106:109], v6 offset:17952
	ds_read_b128 v[110:113], v6 offset:17968
	ds_read_b128 v[114:117], v6 offset:17984
	ds_read2st64_b32 v[206:207], v7 offset0:14 offset1:15
	ds_read_b128 v[208:211], v8 offset:112
	s_waitcnt lgkmcnt(13)
	v_pk_mul_f32 v[10:11], v[2:3], v[58:59] op_sel_hi:[0,1]
	v_pk_fma_f32 v[10:11], v[2:3], v[60:61], v[10:11] op_sel:[1,0,0] op_sel_hi:[1,1,1]
	v_pk_fma_f32 v[10:11], v[4:5], v[62:63], v[10:11] op_sel_hi:[0,1,1]
	v_pk_fma_f32 v[10:11], v[4:5], v[64:65], v[10:11] op_sel:[1,0,0] op_sel_hi:[1,1,1]
	v_fma_f32 v28, v120, v10, v11
	v_pk_mul_f32 v[18:19], v[74:75], v[118:119] op_sel_hi:[1,0]
	v_add_f32_dpp v10, v10, v10 quad_perm:[1,0,3,2] row_mask:0xf bank_mask:0xf bound_ctrl:1
	v_pk_mul_f32 v[20:21], v[76:77], v[118:119] op_sel_hi:[1,0]
	v_pk_fma_f32 v[18:19], v[2:3], v[66:67], v[18:19]
	v_add_f32_dpp v10, v10, v10 quad_perm:[2,3,0,1] row_mask:0xf bank_mask:0xf bound_ctrl:1
	v_pk_fma_f32 v[20:21], v[4:5], v[68:69], v[20:21]
	v_cndmask_b32_e64 v32, v24, v25, s[98:99]
	v_add_f32_dpp v10, v10, v10 row_half_mirror row_mask:0xf bank_mask:0xf bound_ctrl:1
	v_cndmask_b32_e64 v33, v25, v24, s[98:99]
	v_cndmask_b32_e64 v23, v26, v27, s[98:99]
	v_add_f32_dpp v10, v10, v10 row_mirror row_mask:0xf bank_mask:0xf bound_ctrl:1
	v_pk_fma_f32 v[2:3], v[70:71], v[10:11], v[18:19] op_sel_hi:[1,0,1]
	v_pk_fma_f32 v[4:5], v[72:73], v[10:11], v[20:21] op_sel_hi:[1,0,1]
	ds_read_b128 v[186:189], v6 offset:19200
	ds_read_b128 v[190:193], v6 offset:19216
	ds_read_b128 v[194:197], v6 offset:19232
	ds_read_b128 v[198:201], v6 offset:19248
	ds_read_b128 v[202:205], v6 offset:19264
	s_waitcnt lgkmcnt(13)
	v_pk_mul_f32 v[12:13], v[2:3], v[78:79] op_sel_hi:[0,1]
	v_pk_fma_f32 v[12:13], v[2:3], v[80:81], v[12:13] op_sel:[1,0,0] op_sel_hi:[1,1,1]
	v_pk_fma_f32 v[12:13], v[4:5], v[82:83], v[12:13] op_sel_hi:[0,1,1]
	v_pk_fma_f32 v[12:13], v[4:5], v[84:85], v[12:13] op_sel:[1,0,0] op_sel_hi:[1,1,1]
	v_fma_f32 v29, v122, v12, v13
	v_pk_mul_f32 v[18:19], v[94:95], v[118:119] op_sel:[0,1] op_sel_hi:[1,1]
	v_add_f32_dpp v12, v12, v12 quad_perm:[1,0,3,2] row_mask:0xf bank_mask:0xf bound_ctrl:1
	v_pk_mul_f32 v[20:21], v[96:97], v[118:119] op_sel:[0,1] op_sel_hi:[1,1]
	v_pk_fma_f32 v[18:19], v[2:3], v[86:87], v[18:19]
	v_add_f32_dpp v12, v12, v12 quad_perm:[2,3,0,1] row_mask:0xf bank_mask:0xf bound_ctrl:1
	v_pk_fma_f32 v[20:21], v[4:5], v[88:89], v[20:21]
	v_cndmask_b32_e64 v57, v27, v26, s[98:99]
	v_add_f32_dpp v12, v12, v12 row_half_mirror row_mask:0xf bank_mask:0xf bound_ctrl:1
	v_add_f32_dpp v32, v33, v32 quad_perm:[1,0,3,2] row_mask:0xf bank_mask:0xf bound_ctrl:1
	v_add_f32_dpp v23, v57, v23 quad_perm:[1,0,3,2] row_mask:0xf bank_mask:0xf bound_ctrl:1
	v_add_f32_dpp v12, v12, v12 row_mirror row_mask:0xf bank_mask:0xf bound_ctrl:1
	v_pk_fma_f32 v[2:3], v[90:91], v[12:13], v[18:19] op_sel_hi:[1,0,1]
	v_pk_fma_f32 v[4:5], v[92:93], v[12:13], v[20:21] op_sel_hi:[1,0,1]
	ds_read_b128 v[58:61], v6 offset:20480
	ds_read_b128 v[62:65], v6 offset:20496
	ds_read_b128 v[66:69], v6 offset:20512
	ds_read_b128 v[70:73], v6 offset:20528
	ds_read_b128 v[74:77], v6 offset:20544
	ds_read2st64_b32 v[118:119], v7 offset0:16 offset1:17
	ds_read_b128 v[120:123], v8 offset:128
	s_waitcnt lgkmcnt(12)
	v_pk_mul_f32 v[14:15], v[2:3], v[98:99] op_sel_hi:[0,1]
	v_pk_fma_f32 v[14:15], v[2:3], v[100:101], v[14:15] op_sel:[1,0,0] op_sel_hi:[1,1,1]
	v_pk_fma_f32 v[14:15], v[4:5], v[102:103], v[14:15] op_sel_hi:[0,1,1]
	v_pk_fma_f32 v[14:15], v[4:5], v[104:105], v[14:15] op_sel:[1,0,0] op_sel_hi:[1,1,1]
	v_fma_f32 v30, v208, v14, v15
	v_pk_mul_f32 v[18:19], v[114:115], v[206:207] op_sel_hi:[1,0]
	v_add_f32_dpp v14, v14, v14 quad_perm:[1,0,3,2] row_mask:0xf bank_mask:0xf bound_ctrl:1
	v_pk_mul_f32 v[20:21], v[116:117], v[206:207] op_sel_hi:[1,0]
	v_pk_fma_f32 v[18:19], v[2:3], v[106:107], v[18:19]
	v_add_f32_dpp v14, v14, v14 quad_perm:[2,3,0,1] row_mask:0xf bank_mask:0xf bound_ctrl:1
	v_pk_fma_f32 v[20:21], v[4:5], v[108:109], v[20:21]
	v_cndmask_b32_e64 v57, v23, v32, s[100:101]
	v_add_f32_dpp v14, v14, v14 row_half_mirror row_mask:0xf bank_mask:0xf bound_ctrl:1
	v_cndmask_b32_e64 v33, v32, v23, s[100:101]
	v_add_f32_dpp v33, v57, v33 quad_perm:[2,3,0,1] row_mask:0xf bank_mask:0xf bound_ctrl:1
	v_add_f32_dpp v14, v14, v14 row_mirror row_mask:0xf bank_mask:0xf bound_ctrl:1
	v_pk_fma_f32 v[2:3], v[110:111], v[14:15], v[18:19] op_sel_hi:[1,0,1]
	v_pk_fma_f32 v[4:5], v[112:113], v[14:15], v[20:21] op_sel_hi:[1,0,1]
	ds_read_b128 v[78:81], v6 offset:21760
	ds_read_b128 v[82:85], v6 offset:21776
	ds_read_b128 v[86:89], v6 offset:21792
	ds_read_b128 v[90:93], v6 offset:21808
	ds_read_b128 v[94:97], v6 offset:21824
	s_waitcnt lgkmcnt(12)
	v_pk_mul_f32 v[16:17], v[2:3], v[186:187] op_sel_hi:[0,1]
	v_pk_fma_f32 v[16:17], v[2:3], v[188:189], v[16:17] op_sel:[1,0,0] op_sel_hi:[1,1,1]
	v_pk_fma_f32 v[16:17], v[4:5], v[190:191], v[16:17] op_sel_hi:[0,1,1]
	v_pk_fma_f32 v[16:17], v[4:5], v[192:193], v[16:17] op_sel:[1,0,0] op_sel_hi:[1,1,1]
	v_fma_f32 v31, v210, v16, v17
	v_pk_mul_f32 v[18:19], v[202:203], v[206:207] op_sel:[0,1] op_sel_hi:[1,1]
	v_add_f32_dpp v16, v16, v16 quad_perm:[1,0,3,2] row_mask:0xf bank_mask:0xf bound_ctrl:1
	v_pk_mul_f32 v[20:21], v[204:205], v[206:207] op_sel:[0,1] op_sel_hi:[1,1]
	v_pk_fma_f32 v[18:19], v[2:3], v[194:195], v[18:19]
	v_add_f32_dpp v16, v16, v16 quad_perm:[2,3,0,1] row_mask:0xf bank_mask:0xf bound_ctrl:1
	v_pk_fma_f32 v[20:21], v[4:5], v[196:197], v[20:21]
	v_add_f32_dpp v33, v33, v33 row_ror:4 row_mask:0xf bank_mask:0xf bound_ctrl:1
	v_add_f32_dpp v16, v16, v16 row_half_mirror row_mask:0xf bank_mask:0xf bound_ctrl:1
	s_nop 0
	v_add_f32_dpp v33, v33, v33 row_ror:8 row_mask:0xf bank_mask:0xf bound_ctrl:1
	v_add_f32_dpp v16, v16, v16 row_mirror row_mask:0xf bank_mask:0xf bound_ctrl:1
	v_pk_fma_f32 v[2:3], v[198:199], v[16:17], v[18:19] op_sel_hi:[1,0,1]
	v_pk_fma_f32 v[4:5], v[200:201], v[16:17], v[20:21] op_sel_hi:[1,0,1]
	ds_write_b32 v56, v33 offset:512
	ds_read_b128 v[98:101], v6 offset:23040
	ds_read_b128 v[102:105], v6 offset:23056
	ds_read_b128 v[106:109], v6 offset:23072
	ds_read_b128 v[110:113], v6 offset:23088
	ds_read_b128 v[114:117], v6 offset:23104
	ds_read2st64_b32 v[206:207], v7 offset0:18 offset1:19
	ds_read_b128 v[208:211], v8 offset:144
	s_waitcnt lgkmcnt(13)
	v_pk_mul_f32 v[10:11], v[2:3], v[58:59] op_sel_hi:[0,1]
	v_pk_fma_f32 v[10:11], v[2:3], v[60:61], v[10:11] op_sel:[1,0,0] op_sel_hi:[1,1,1]
	v_pk_fma_f32 v[10:11], v[4:5], v[62:63], v[10:11] op_sel_hi:[0,1,1]
	v_pk_fma_f32 v[10:11], v[4:5], v[64:65], v[10:11] op_sel:[1,0,0] op_sel_hi:[1,1,1]
	v_fma_f32 v24, v120, v10, v11
	v_pk_mul_f32 v[18:19], v[74:75], v[118:119] op_sel_hi:[1,0]
	v_add_f32_dpp v10, v10, v10 quad_perm:[1,0,3,2] row_mask:0xf bank_mask:0xf bound_ctrl:1
	v_pk_mul_f32 v[20:21], v[76:77], v[118:119] op_sel_hi:[1,0]
	v_pk_fma_f32 v[18:19], v[2:3], v[66:67], v[18:19]
	v_add_f32_dpp v10, v10, v10 quad_perm:[2,3,0,1] row_mask:0xf bank_mask:0xf bound_ctrl:1
	v_pk_fma_f32 v[20:21], v[4:5], v[68:69], v[20:21]
	v_cndmask_b32_e64 v32, v28, v29, s[98:99]
	v_add_f32_dpp v10, v10, v10 row_half_mirror row_mask:0xf bank_mask:0xf bound_ctrl:1
	v_cndmask_b32_e64 v33, v29, v28, s[98:99]
	v_cndmask_b32_e64 v23, v30, v31, s[98:99]
	v_add_f32_dpp v10, v10, v10 row_mirror row_mask:0xf bank_mask:0xf bound_ctrl:1
	v_pk_fma_f32 v[2:3], v[70:71], v[10:11], v[18:19] op_sel_hi:[1,0,1]
	v_pk_fma_f32 v[4:5], v[72:73], v[10:11], v[20:21] op_sel_hi:[1,0,1]
	ds_read_b128 v[186:189], v6 offset:24320
	ds_read_b128 v[190:193], v6 offset:24336
	ds_read_b128 v[194:197], v6 offset:24352
	ds_read_b128 v[198:201], v6 offset:24368
	ds_read_b128 v[202:205], v6 offset:24384
	s_waitcnt lgkmcnt(13)
	v_pk_mul_f32 v[12:13], v[2:3], v[78:79] op_sel_hi:[0,1]
	v_pk_fma_f32 v[12:13], v[2:3], v[80:81], v[12:13] op_sel:[1,0,0] op_sel_hi:[1,1,1]
	v_pk_fma_f32 v[12:13], v[4:5], v[82:83], v[12:13] op_sel_hi:[0,1,1]
	v_pk_fma_f32 v[12:13], v[4:5], v[84:85], v[12:13] op_sel:[1,0,0] op_sel_hi:[1,1,1]
	v_fma_f32 v25, v122, v12, v13
	v_pk_mul_f32 v[18:19], v[94:95], v[118:119] op_sel:[0,1] op_sel_hi:[1,1]
	v_add_f32_dpp v12, v12, v12 quad_perm:[1,0,3,2] row_mask:0xf bank_mask:0xf bound_ctrl:1
	v_pk_mul_f32 v[20:21], v[96:97], v[118:119] op_sel:[0,1] op_sel_hi:[1,1]
	v_pk_fma_f32 v[18:19], v[2:3], v[86:87], v[18:19]
	v_add_f32_dpp v12, v12, v12 quad_perm:[2,3,0,1] row_mask:0xf bank_mask:0xf bound_ctrl:1
	v_pk_fma_f32 v[20:21], v[4:5], v[88:89], v[20:21]
	v_cndmask_b32_e64 v57, v31, v30, s[98:99]
	v_add_f32_dpp v12, v12, v12 row_half_mirror row_mask:0xf bank_mask:0xf bound_ctrl:1
	v_add_f32_dpp v32, v33, v32 quad_perm:[1,0,3,2] row_mask:0xf bank_mask:0xf bound_ctrl:1
	v_add_f32_dpp v23, v57, v23 quad_perm:[1,0,3,2] row_mask:0xf bank_mask:0xf bound_ctrl:1
	v_add_f32_dpp v12, v12, v12 row_mirror row_mask:0xf bank_mask:0xf bound_ctrl:1
	v_pk_fma_f32 v[2:3], v[90:91], v[12:13], v[18:19] op_sel_hi:[1,0,1]
	v_pk_fma_f32 v[4:5], v[92:93], v[12:13], v[20:21] op_sel_hi:[1,0,1]
	ds_read_b128 v[58:61], v6 offset:25600
	ds_read_b128 v[62:65], v6 offset:25616
	ds_read_b128 v[66:69], v6 offset:25632
	ds_read_b128 v[70:73], v6 offset:25648
	ds_read_b128 v[74:77], v6 offset:25664
	ds_read2st64_b32 v[118:119], v7 offset0:20 offset1:21
	ds_read_b128 v[120:123], v8 offset:160
	s_waitcnt lgkmcnt(12)
	v_pk_mul_f32 v[14:15], v[2:3], v[98:99] op_sel_hi:[0,1]
	v_pk_fma_f32 v[14:15], v[2:3], v[100:101], v[14:15] op_sel:[1,0,0] op_sel_hi:[1,1,1]
	v_pk_fma_f32 v[14:15], v[4:5], v[102:103], v[14:15] op_sel_hi:[0,1,1]
	v_pk_fma_f32 v[14:15], v[4:5], v[104:105], v[14:15] op_sel:[1,0,0] op_sel_hi:[1,1,1]
	v_fma_f32 v26, v208, v14, v15
	v_pk_mul_f32 v[18:19], v[114:115], v[206:207] op_sel_hi:[1,0]
	v_add_f32_dpp v14, v14, v14 quad_perm:[1,0,3,2] row_mask:0xf bank_mask:0xf bound_ctrl:1
	v_pk_mul_f32 v[20:21], v[116:117], v[206:207] op_sel_hi:[1,0]
	v_pk_fma_f32 v[18:19], v[2:3], v[106:107], v[18:19]
	v_add_f32_dpp v14, v14, v14 quad_perm:[2,3,0,1] row_mask:0xf bank_mask:0xf bound_ctrl:1
	v_pk_fma_f32 v[20:21], v[4:5], v[108:109], v[20:21]
	v_cndmask_b32_e64 v57, v23, v32, s[100:101]
	v_add_f32_dpp v14, v14, v14 row_half_mirror row_mask:0xf bank_mask:0xf bound_ctrl:1
	v_cndmask_b32_e64 v33, v32, v23, s[100:101]
	v_add_f32_dpp v33, v57, v33 quad_perm:[2,3,0,1] row_mask:0xf bank_mask:0xf bound_ctrl:1
	v_add_f32_dpp v14, v14, v14 row_mirror row_mask:0xf bank_mask:0xf bound_ctrl:1
	v_pk_fma_f32 v[2:3], v[110:111], v[14:15], v[18:19] op_sel_hi:[1,0,1]
	v_pk_fma_f32 v[4:5], v[112:113], v[14:15], v[20:21] op_sel_hi:[1,0,1]
	ds_read_b128 v[78:81], v6 offset:26880
	ds_read_b128 v[82:85], v6 offset:26896
	ds_read_b128 v[86:89], v6 offset:26912
	ds_read_b128 v[90:93], v6 offset:26928
	ds_read_b128 v[94:97], v6 offset:26944
	s_waitcnt lgkmcnt(12)
	v_pk_mul_f32 v[16:17], v[2:3], v[186:187] op_sel_hi:[0,1]
	v_pk_fma_f32 v[16:17], v[2:3], v[188:189], v[16:17] op_sel:[1,0,0] op_sel_hi:[1,1,1]
	v_pk_fma_f32 v[16:17], v[4:5], v[190:191], v[16:17] op_sel_hi:[0,1,1]
	v_pk_fma_f32 v[16:17], v[4:5], v[192:193], v[16:17] op_sel:[1,0,0] op_sel_hi:[1,1,1]
	v_fma_f32 v27, v210, v16, v17
	v_pk_mul_f32 v[18:19], v[202:203], v[206:207] op_sel:[0,1] op_sel_hi:[1,1]
	v_add_f32_dpp v16, v16, v16 quad_perm:[1,0,3,2] row_mask:0xf bank_mask:0xf bound_ctrl:1
	v_pk_mul_f32 v[20:21], v[204:205], v[206:207] op_sel:[0,1] op_sel_hi:[1,1]
	v_pk_fma_f32 v[18:19], v[2:3], v[194:195], v[18:19]
	v_add_f32_dpp v16, v16, v16 quad_perm:[2,3,0,1] row_mask:0xf bank_mask:0xf bound_ctrl:1
	v_pk_fma_f32 v[20:21], v[4:5], v[196:197], v[20:21]
	v_add_f32_dpp v33, v33, v33 row_ror:4 row_mask:0xf bank_mask:0xf bound_ctrl:1
	v_add_f32_dpp v16, v16, v16 row_half_mirror row_mask:0xf bank_mask:0xf bound_ctrl:1
	s_nop 0
	v_add_f32_dpp v33, v33, v33 row_ror:8 row_mask:0xf bank_mask:0xf bound_ctrl:1
	v_add_f32_dpp v16, v16, v16 row_mirror row_mask:0xf bank_mask:0xf bound_ctrl:1
	v_pk_fma_f32 v[2:3], v[198:199], v[16:17], v[18:19] op_sel_hi:[1,0,1]
	v_pk_fma_f32 v[4:5], v[200:201], v[16:17], v[20:21] op_sel_hi:[1,0,1]
	ds_write_b32 v56, v33 offset:768
	ds_read_b128 v[98:101], v6 offset:28160
	ds_read_b128 v[102:105], v6 offset:28176
	ds_read_b128 v[106:109], v6 offset:28192
	ds_read_b128 v[110:113], v6 offset:28208
	ds_read_b128 v[114:117], v6 offset:28224
	ds_read2st64_b32 v[206:207], v7 offset0:22 offset1:23
	ds_read_b128 v[208:211], v8 offset:176
	s_waitcnt lgkmcnt(13)
	v_pk_mul_f32 v[10:11], v[2:3], v[58:59] op_sel_hi:[0,1]
	v_pk_fma_f32 v[10:11], v[2:3], v[60:61], v[10:11] op_sel:[1,0,0] op_sel_hi:[1,1,1]
	v_pk_fma_f32 v[10:11], v[4:5], v[62:63], v[10:11] op_sel_hi:[0,1,1]
	v_pk_fma_f32 v[10:11], v[4:5], v[64:65], v[10:11] op_sel:[1,0,0] op_sel_hi:[1,1,1]
	v_fma_f32 v28, v120, v10, v11
	v_pk_mul_f32 v[18:19], v[74:75], v[118:119] op_sel_hi:[1,0]
	v_add_f32_dpp v10, v10, v10 quad_perm:[1,0,3,2] row_mask:0xf bank_mask:0xf bound_ctrl:1
	v_pk_mul_f32 v[20:21], v[76:77], v[118:119] op_sel_hi:[1,0]
	v_pk_fma_f32 v[18:19], v[2:3], v[66:67], v[18:19]
	v_add_f32_dpp v10, v10, v10 quad_perm:[2,3,0,1] row_mask:0xf bank_mask:0xf bound_ctrl:1
	v_pk_fma_f32 v[20:21], v[4:5], v[68:69], v[20:21]
	v_cndmask_b32_e64 v32, v24, v25, s[98:99]
	v_add_f32_dpp v10, v10, v10 row_half_mirror row_mask:0xf bank_mask:0xf bound_ctrl:1
	v_cndmask_b32_e64 v33, v25, v24, s[98:99]
	v_cndmask_b32_e64 v23, v26, v27, s[98:99]
	v_add_f32_dpp v10, v10, v10 row_mirror row_mask:0xf bank_mask:0xf bound_ctrl:1
	v_pk_fma_f32 v[2:3], v[70:71], v[10:11], v[18:19] op_sel_hi:[1,0,1]
	v_pk_fma_f32 v[4:5], v[72:73], v[10:11], v[20:21] op_sel_hi:[1,0,1]
	ds_read_b128 v[186:189], v6 offset:29440
	ds_read_b128 v[190:193], v6 offset:29456
	ds_read_b128 v[194:197], v6 offset:29472
	ds_read_b128 v[198:201], v6 offset:29488
	ds_read_b128 v[202:205], v6 offset:29504
	s_waitcnt lgkmcnt(13)
	v_pk_mul_f32 v[12:13], v[2:3], v[78:79] op_sel_hi:[0,1]
	v_pk_fma_f32 v[12:13], v[2:3], v[80:81], v[12:13] op_sel:[1,0,0] op_sel_hi:[1,1,1]
	v_pk_fma_f32 v[12:13], v[4:5], v[82:83], v[12:13] op_sel_hi:[0,1,1]
	v_pk_fma_f32 v[12:13], v[4:5], v[84:85], v[12:13] op_sel:[1,0,0] op_sel_hi:[1,1,1]
	v_fma_f32 v29, v122, v12, v13
	v_pk_mul_f32 v[18:19], v[94:95], v[118:119] op_sel:[0,1] op_sel_hi:[1,1]
	v_add_f32_dpp v12, v12, v12 quad_perm:[1,0,3,2] row_mask:0xf bank_mask:0xf bound_ctrl:1
	v_pk_mul_f32 v[20:21], v[96:97], v[118:119] op_sel:[0,1] op_sel_hi:[1,1]
	v_pk_fma_f32 v[18:19], v[2:3], v[86:87], v[18:19]
	v_add_f32_dpp v12, v12, v12 quad_perm:[2,3,0,1] row_mask:0xf bank_mask:0xf bound_ctrl:1
	v_pk_fma_f32 v[20:21], v[4:5], v[88:89], v[20:21]
	v_cndmask_b32_e64 v57, v27, v26, s[98:99]
	v_add_f32_dpp v12, v12, v12 row_half_mirror row_mask:0xf bank_mask:0xf bound_ctrl:1
	v_add_f32_dpp v32, v33, v32 quad_perm:[1,0,3,2] row_mask:0xf bank_mask:0xf bound_ctrl:1
	v_add_f32_dpp v23, v57, v23 quad_perm:[1,0,3,2] row_mask:0xf bank_mask:0xf bound_ctrl:1
	v_add_f32_dpp v12, v12, v12 row_mirror row_mask:0xf bank_mask:0xf bound_ctrl:1
	v_pk_fma_f32 v[2:3], v[90:91], v[12:13], v[18:19] op_sel_hi:[1,0,1]
	v_pk_fma_f32 v[4:5], v[92:93], v[12:13], v[20:21] op_sel_hi:[1,0,1]
	ds_read_b128 v[58:61], v6 offset:30720
	ds_read_b128 v[62:65], v6 offset:30736
	ds_read_b128 v[66:69], v6 offset:30752
	ds_read_b128 v[70:73], v6 offset:30768
	ds_read_b128 v[74:77], v6 offset:30784
	ds_read2st64_b32 v[118:119], v7 offset0:24 offset1:25
	ds_read_b128 v[120:123], v8 offset:192
	s_waitcnt lgkmcnt(12)
	v_pk_mul_f32 v[14:15], v[2:3], v[98:99] op_sel_hi:[0,1]
	v_pk_fma_f32 v[14:15], v[2:3], v[100:101], v[14:15] op_sel:[1,0,0] op_sel_hi:[1,1,1]
	v_pk_fma_f32 v[14:15], v[4:5], v[102:103], v[14:15] op_sel_hi:[0,1,1]
	v_pk_fma_f32 v[14:15], v[4:5], v[104:105], v[14:15] op_sel:[1,0,0] op_sel_hi:[1,1,1]
	v_fma_f32 v30, v208, v14, v15
	v_pk_mul_f32 v[18:19], v[114:115], v[206:207] op_sel_hi:[1,0]
	v_add_f32_dpp v14, v14, v14 quad_perm:[1,0,3,2] row_mask:0xf bank_mask:0xf bound_ctrl:1
	v_pk_mul_f32 v[20:21], v[116:117], v[206:207] op_sel_hi:[1,0]
	v_pk_fma_f32 v[18:19], v[2:3], v[106:107], v[18:19]
	v_add_f32_dpp v14, v14, v14 quad_perm:[2,3,0,1] row_mask:0xf bank_mask:0xf bound_ctrl:1
	v_pk_fma_f32 v[20:21], v[4:5], v[108:109], v[20:21]
	v_cndmask_b32_e64 v57, v23, v32, s[100:101]
	v_add_f32_dpp v14, v14, v14 row_half_mirror row_mask:0xf bank_mask:0xf bound_ctrl:1
	v_cndmask_b32_e64 v33, v32, v23, s[100:101]
	v_add_f32_dpp v33, v57, v33 quad_perm:[2,3,0,1] row_mask:0xf bank_mask:0xf bound_ctrl:1
	v_add_f32_dpp v14, v14, v14 row_mirror row_mask:0xf bank_mask:0xf bound_ctrl:1
	v_pk_fma_f32 v[2:3], v[110:111], v[14:15], v[18:19] op_sel_hi:[1,0,1]
	v_pk_fma_f32 v[4:5], v[112:113], v[14:15], v[20:21] op_sel_hi:[1,0,1]
	ds_read_b128 v[78:81], v6 offset:32000
	ds_read_b128 v[82:85], v6 offset:32016
	ds_read_b128 v[86:89], v6 offset:32032
	ds_read_b128 v[90:93], v6 offset:32048
	ds_read_b128 v[94:97], v6 offset:32064
	s_waitcnt lgkmcnt(12)
	v_pk_mul_f32 v[16:17], v[2:3], v[186:187] op_sel_hi:[0,1]
	v_pk_fma_f32 v[16:17], v[2:3], v[188:189], v[16:17] op_sel:[1,0,0] op_sel_hi:[1,1,1]
	v_pk_fma_f32 v[16:17], v[4:5], v[190:191], v[16:17] op_sel_hi:[0,1,1]
	v_pk_fma_f32 v[16:17], v[4:5], v[192:193], v[16:17] op_sel:[1,0,0] op_sel_hi:[1,1,1]
	v_fma_f32 v31, v210, v16, v17
	v_pk_mul_f32 v[18:19], v[202:203], v[206:207] op_sel:[0,1] op_sel_hi:[1,1]
	v_add_f32_dpp v16, v16, v16 quad_perm:[1,0,3,2] row_mask:0xf bank_mask:0xf bound_ctrl:1
	v_pk_mul_f32 v[20:21], v[204:205], v[206:207] op_sel:[0,1] op_sel_hi:[1,1]
	v_pk_fma_f32 v[18:19], v[2:3], v[194:195], v[18:19]
	v_add_f32_dpp v16, v16, v16 quad_perm:[2,3,0,1] row_mask:0xf bank_mask:0xf bound_ctrl:1
	v_pk_fma_f32 v[20:21], v[4:5], v[196:197], v[20:21]
	v_add_f32_dpp v33, v33, v33 row_ror:4 row_mask:0xf bank_mask:0xf bound_ctrl:1
	v_add_f32_dpp v16, v16, v16 row_half_mirror row_mask:0xf bank_mask:0xf bound_ctrl:1
	s_nop 0
	v_add_f32_dpp v33, v33, v33 row_ror:8 row_mask:0xf bank_mask:0xf bound_ctrl:1
	v_add_f32_dpp v16, v16, v16 row_mirror row_mask:0xf bank_mask:0xf bound_ctrl:1
	v_pk_fma_f32 v[2:3], v[198:199], v[16:17], v[18:19] op_sel_hi:[1,0,1]
	v_pk_fma_f32 v[4:5], v[200:201], v[16:17], v[20:21] op_sel_hi:[1,0,1]
	ds_write_b32 v56, v33 offset:1024
	ds_read_b128 v[98:101], v6 offset:33280
	ds_read_b128 v[102:105], v6 offset:33296
	ds_read_b128 v[106:109], v6 offset:33312
	ds_read_b128 v[110:113], v6 offset:33328
	ds_read_b128 v[114:117], v6 offset:33344
	ds_read2st64_b32 v[206:207], v7 offset0:26 offset1:27
	ds_read_b128 v[208:211], v8 offset:208
	s_waitcnt lgkmcnt(13)
	v_pk_mul_f32 v[10:11], v[2:3], v[58:59] op_sel_hi:[0,1]
	v_pk_fma_f32 v[10:11], v[2:3], v[60:61], v[10:11] op_sel:[1,0,0] op_sel_hi:[1,1,1]
	v_pk_fma_f32 v[10:11], v[4:5], v[62:63], v[10:11] op_sel_hi:[0,1,1]
	v_pk_fma_f32 v[10:11], v[4:5], v[64:65], v[10:11] op_sel:[1,0,0] op_sel_hi:[1,1,1]
	v_fma_f32 v24, v120, v10, v11
	v_pk_mul_f32 v[18:19], v[74:75], v[118:119] op_sel_hi:[1,0]
	v_add_f32_dpp v10, v10, v10 quad_perm:[1,0,3,2] row_mask:0xf bank_mask:0xf bound_ctrl:1
	v_pk_mul_f32 v[20:21], v[76:77], v[118:119] op_sel_hi:[1,0]
	v_pk_fma_f32 v[18:19], v[2:3], v[66:67], v[18:19]
	v_add_f32_dpp v10, v10, v10 quad_perm:[2,3,0,1] row_mask:0xf bank_mask:0xf bound_ctrl:1
	v_pk_fma_f32 v[20:21], v[4:5], v[68:69], v[20:21]
	v_cndmask_b32_e64 v32, v28, v29, s[98:99]
	v_add_f32_dpp v10, v10, v10 row_half_mirror row_mask:0xf bank_mask:0xf bound_ctrl:1
	v_cndmask_b32_e64 v33, v29, v28, s[98:99]
	v_cndmask_b32_e64 v23, v30, v31, s[98:99]
	v_add_f32_dpp v10, v10, v10 row_mirror row_mask:0xf bank_mask:0xf bound_ctrl:1
	v_pk_fma_f32 v[2:3], v[70:71], v[10:11], v[18:19] op_sel_hi:[1,0,1]
	v_pk_fma_f32 v[4:5], v[72:73], v[10:11], v[20:21] op_sel_hi:[1,0,1]
	ds_read_b128 v[186:189], v6 offset:34560
	ds_read_b128 v[190:193], v6 offset:34576
	ds_read_b128 v[194:197], v6 offset:34592
	ds_read_b128 v[198:201], v6 offset:34608
	ds_read_b128 v[202:205], v6 offset:34624
	s_waitcnt lgkmcnt(13)
	v_pk_mul_f32 v[12:13], v[2:3], v[78:79] op_sel_hi:[0,1]
	v_pk_fma_f32 v[12:13], v[2:3], v[80:81], v[12:13] op_sel:[1,0,0] op_sel_hi:[1,1,1]
	v_pk_fma_f32 v[12:13], v[4:5], v[82:83], v[12:13] op_sel_hi:[0,1,1]
	v_pk_fma_f32 v[12:13], v[4:5], v[84:85], v[12:13] op_sel:[1,0,0] op_sel_hi:[1,1,1]
	v_fma_f32 v25, v122, v12, v13
	v_pk_mul_f32 v[18:19], v[94:95], v[118:119] op_sel:[0,1] op_sel_hi:[1,1]
	v_add_f32_dpp v12, v12, v12 quad_perm:[1,0,3,2] row_mask:0xf bank_mask:0xf bound_ctrl:1
	v_pk_mul_f32 v[20:21], v[96:97], v[118:119] op_sel:[0,1] op_sel_hi:[1,1]
	v_pk_fma_f32 v[18:19], v[2:3], v[86:87], v[18:19]
	v_add_f32_dpp v12, v12, v12 quad_perm:[2,3,0,1] row_mask:0xf bank_mask:0xf bound_ctrl:1
	v_pk_fma_f32 v[20:21], v[4:5], v[88:89], v[20:21]
	v_cndmask_b32_e64 v57, v31, v30, s[98:99]
	v_add_f32_dpp v12, v12, v12 row_half_mirror row_mask:0xf bank_mask:0xf bound_ctrl:1
	v_add_f32_dpp v32, v33, v32 quad_perm:[1,0,3,2] row_mask:0xf bank_mask:0xf bound_ctrl:1
	v_add_f32_dpp v23, v57, v23 quad_perm:[1,0,3,2] row_mask:0xf bank_mask:0xf bound_ctrl:1
	v_add_f32_dpp v12, v12, v12 row_mirror row_mask:0xf bank_mask:0xf bound_ctrl:1
	v_pk_fma_f32 v[2:3], v[90:91], v[12:13], v[18:19] op_sel_hi:[1,0,1]
	v_pk_fma_f32 v[4:5], v[92:93], v[12:13], v[20:21] op_sel_hi:[1,0,1]
	ds_read_b128 v[58:61], v6 offset:35840
	ds_read_b128 v[62:65], v6 offset:35856
	ds_read_b128 v[66:69], v6 offset:35872
	ds_read_b128 v[70:73], v6 offset:35888
	ds_read_b128 v[74:77], v6 offset:35904
	ds_read2st64_b32 v[118:119], v7 offset0:28 offset1:29
	ds_read_b128 v[120:123], v8 offset:224
	s_waitcnt lgkmcnt(12)
	v_pk_mul_f32 v[14:15], v[2:3], v[98:99] op_sel_hi:[0,1]
	v_pk_fma_f32 v[14:15], v[2:3], v[100:101], v[14:15] op_sel:[1,0,0] op_sel_hi:[1,1,1]
	v_pk_fma_f32 v[14:15], v[4:5], v[102:103], v[14:15] op_sel_hi:[0,1,1]
	v_pk_fma_f32 v[14:15], v[4:5], v[104:105], v[14:15] op_sel:[1,0,0] op_sel_hi:[1,1,1]
	v_fma_f32 v26, v208, v14, v15
	v_pk_mul_f32 v[18:19], v[114:115], v[206:207] op_sel_hi:[1,0]
	v_add_f32_dpp v14, v14, v14 quad_perm:[1,0,3,2] row_mask:0xf bank_mask:0xf bound_ctrl:1
	v_pk_mul_f32 v[20:21], v[116:117], v[206:207] op_sel_hi:[1,0]
	v_pk_fma_f32 v[18:19], v[2:3], v[106:107], v[18:19]
	v_add_f32_dpp v14, v14, v14 quad_perm:[2,3,0,1] row_mask:0xf bank_mask:0xf bound_ctrl:1
	v_pk_fma_f32 v[20:21], v[4:5], v[108:109], v[20:21]
	v_cndmask_b32_e64 v57, v23, v32, s[100:101]
	v_add_f32_dpp v14, v14, v14 row_half_mirror row_mask:0xf bank_mask:0xf bound_ctrl:1
	v_cndmask_b32_e64 v33, v32, v23, s[100:101]
	v_add_f32_dpp v33, v57, v33 quad_perm:[2,3,0,1] row_mask:0xf bank_mask:0xf bound_ctrl:1
	v_add_f32_dpp v14, v14, v14 row_mirror row_mask:0xf bank_mask:0xf bound_ctrl:1
	v_pk_fma_f32 v[2:3], v[110:111], v[14:15], v[18:19] op_sel_hi:[1,0,1]
	v_pk_fma_f32 v[4:5], v[112:113], v[14:15], v[20:21] op_sel_hi:[1,0,1]
	ds_read_b128 v[78:81], v6 offset:37120
	ds_read_b128 v[82:85], v6 offset:37136
	ds_read_b128 v[86:89], v6 offset:37152
	ds_read_b128 v[90:93], v6 offset:37168
	ds_read_b128 v[94:97], v6 offset:37184
	s_waitcnt lgkmcnt(12)
	v_pk_mul_f32 v[16:17], v[2:3], v[186:187] op_sel_hi:[0,1]
	v_pk_fma_f32 v[16:17], v[2:3], v[188:189], v[16:17] op_sel:[1,0,0] op_sel_hi:[1,1,1]
	v_pk_fma_f32 v[16:17], v[4:5], v[190:191], v[16:17] op_sel_hi:[0,1,1]
	v_pk_fma_f32 v[16:17], v[4:5], v[192:193], v[16:17] op_sel:[1,0,0] op_sel_hi:[1,1,1]
	v_fma_f32 v27, v210, v16, v17
	v_pk_mul_f32 v[18:19], v[202:203], v[206:207] op_sel:[0,1] op_sel_hi:[1,1]
	v_add_f32_dpp v16, v16, v16 quad_perm:[1,0,3,2] row_mask:0xf bank_mask:0xf bound_ctrl:1
	v_pk_mul_f32 v[20:21], v[204:205], v[206:207] op_sel:[0,1] op_sel_hi:[1,1]
	v_pk_fma_f32 v[18:19], v[2:3], v[194:195], v[18:19]
	v_add_f32_dpp v16, v16, v16 quad_perm:[2,3,0,1] row_mask:0xf bank_mask:0xf bound_ctrl:1
	v_pk_fma_f32 v[20:21], v[4:5], v[196:197], v[20:21]
	v_add_f32_dpp v33, v33, v33 row_ror:4 row_mask:0xf bank_mask:0xf bound_ctrl:1
	v_add_f32_dpp v16, v16, v16 row_half_mirror row_mask:0xf bank_mask:0xf bound_ctrl:1
	s_nop 0
	v_add_f32_dpp v33, v33, v33 row_ror:8 row_mask:0xf bank_mask:0xf bound_ctrl:1
	v_add_f32_dpp v16, v16, v16 row_mirror row_mask:0xf bank_mask:0xf bound_ctrl:1
	v_pk_fma_f32 v[2:3], v[198:199], v[16:17], v[18:19] op_sel_hi:[1,0,1]
	v_pk_fma_f32 v[4:5], v[200:201], v[16:17], v[20:21] op_sel_hi:[1,0,1]
	ds_write_b32 v56, v33 offset:1280
	ds_read_b128 v[98:101], v6 offset:38400
	ds_read_b128 v[102:105], v6 offset:38416
	ds_read_b128 v[106:109], v6 offset:38432
	ds_read_b128 v[110:113], v6 offset:38448
	ds_read_b128 v[114:117], v6 offset:38464
	ds_read2st64_b32 v[206:207], v7 offset0:30 offset1:31
	ds_read_b128 v[208:211], v8 offset:240
	s_waitcnt lgkmcnt(13)
	v_pk_mul_f32 v[10:11], v[2:3], v[58:59] op_sel_hi:[0,1]
	v_pk_fma_f32 v[10:11], v[2:3], v[60:61], v[10:11] op_sel:[1,0,0] op_sel_hi:[1,1,1]
	v_pk_fma_f32 v[10:11], v[4:5], v[62:63], v[10:11] op_sel_hi:[0,1,1]
	v_pk_fma_f32 v[10:11], v[4:5], v[64:65], v[10:11] op_sel:[1,0,0] op_sel_hi:[1,1,1]
	v_fma_f32 v28, v120, v10, v11
	v_pk_mul_f32 v[18:19], v[74:75], v[118:119] op_sel_hi:[1,0]
	v_add_f32_dpp v10, v10, v10 quad_perm:[1,0,3,2] row_mask:0xf bank_mask:0xf bound_ctrl:1
	v_pk_mul_f32 v[20:21], v[76:77], v[118:119] op_sel_hi:[1,0]
	v_pk_fma_f32 v[18:19], v[2:3], v[66:67], v[18:19]
	v_add_f32_dpp v10, v10, v10 quad_perm:[2,3,0,1] row_mask:0xf bank_mask:0xf bound_ctrl:1
	v_pk_fma_f32 v[20:21], v[4:5], v[68:69], v[20:21]
	v_cndmask_b32_e64 v32, v24, v25, s[98:99]
	v_add_f32_dpp v10, v10, v10 row_half_mirror row_mask:0xf bank_mask:0xf bound_ctrl:1
	v_cndmask_b32_e64 v33, v25, v24, s[98:99]
	v_cndmask_b32_e64 v23, v26, v27, s[98:99]
	v_add_f32_dpp v10, v10, v10 row_mirror row_mask:0xf bank_mask:0xf bound_ctrl:1
	v_pk_fma_f32 v[2:3], v[70:71], v[10:11], v[18:19] op_sel_hi:[1,0,1]
	v_pk_fma_f32 v[4:5], v[72:73], v[10:11], v[20:21] op_sel_hi:[1,0,1]
	ds_read_b128 v[186:189], v6 offset:39680
	ds_read_b128 v[190:193], v6 offset:39696
	ds_read_b128 v[194:197], v6 offset:39712
	ds_read_b128 v[198:201], v6 offset:39728
	ds_read_b128 v[202:205], v6 offset:39744
	s_waitcnt lgkmcnt(13)
	v_pk_mul_f32 v[12:13], v[2:3], v[78:79] op_sel_hi:[0,1]
	v_pk_fma_f32 v[12:13], v[2:3], v[80:81], v[12:13] op_sel:[1,0,0] op_sel_hi:[1,1,1]
	v_pk_fma_f32 v[12:13], v[4:5], v[82:83], v[12:13] op_sel_hi:[0,1,1]
	v_pk_fma_f32 v[12:13], v[4:5], v[84:85], v[12:13] op_sel:[1,0,0] op_sel_hi:[1,1,1]
	v_fma_f32 v29, v122, v12, v13
	v_pk_mul_f32 v[18:19], v[94:95], v[118:119] op_sel:[0,1] op_sel_hi:[1,1]
	v_add_f32_dpp v12, v12, v12 quad_perm:[1,0,3,2] row_mask:0xf bank_mask:0xf bound_ctrl:1
	v_pk_mul_f32 v[20:21], v[96:97], v[118:119] op_sel:[0,1] op_sel_hi:[1,1]
	v_pk_fma_f32 v[18:19], v[2:3], v[86:87], v[18:19]
	v_add_f32_dpp v12, v12, v12 quad_perm:[2,3,0,1] row_mask:0xf bank_mask:0xf bound_ctrl:1
	v_pk_fma_f32 v[20:21], v[4:5], v[88:89], v[20:21]
	v_cndmask_b32_e64 v57, v27, v26, s[98:99]
	v_add_f32_dpp v12, v12, v12 row_half_mirror row_mask:0xf bank_mask:0xf bound_ctrl:1
	v_add_f32_dpp v32, v33, v32 quad_perm:[1,0,3,2] row_mask:0xf bank_mask:0xf bound_ctrl:1
	v_add_f32_dpp v23, v57, v23 quad_perm:[1,0,3,2] row_mask:0xf bank_mask:0xf bound_ctrl:1
	v_add_f32_dpp v12, v12, v12 row_mirror row_mask:0xf bank_mask:0xf bound_ctrl:1
	v_pk_fma_f32 v[2:3], v[90:91], v[12:13], v[18:19] op_sel_hi:[1,0,1]
	v_pk_fma_f32 v[4:5], v[92:93], v[12:13], v[20:21] op_sel_hi:[1,0,1]
	s_waitcnt lgkmcnt(5)
	v_pk_mul_f32 v[14:15], v[2:3], v[98:99] op_sel_hi:[0,1]
	v_pk_fma_f32 v[14:15], v[2:3], v[100:101], v[14:15] op_sel:[1,0,0] op_sel_hi:[1,1,1]
	v_pk_fma_f32 v[14:15], v[4:5], v[102:103], v[14:15] op_sel_hi:[0,1,1]
	v_pk_fma_f32 v[14:15], v[4:5], v[104:105], v[14:15] op_sel:[1,0,0] op_sel_hi:[1,1,1]
	v_fma_f32 v30, v208, v14, v15
	v_pk_mul_f32 v[18:19], v[114:115], v[206:207] op_sel_hi:[1,0]
	v_add_f32_dpp v14, v14, v14 quad_perm:[1,0,3,2] row_mask:0xf bank_mask:0xf bound_ctrl:1
	v_pk_mul_f32 v[20:21], v[116:117], v[206:207] op_sel_hi:[1,0]
	v_pk_fma_f32 v[18:19], v[2:3], v[106:107], v[18:19]
	v_add_f32_dpp v14, v14, v14 quad_perm:[2,3,0,1] row_mask:0xf bank_mask:0xf bound_ctrl:1
	v_pk_fma_f32 v[20:21], v[4:5], v[108:109], v[20:21]
	v_cndmask_b32_e64 v57, v23, v32, s[100:101]
	v_add_f32_dpp v14, v14, v14 row_half_mirror row_mask:0xf bank_mask:0xf bound_ctrl:1
	v_cndmask_b32_e64 v33, v32, v23, s[100:101]
	v_add_f32_dpp v33, v57, v33 quad_perm:[2,3,0,1] row_mask:0xf bank_mask:0xf bound_ctrl:1
	v_add_f32_dpp v14, v14, v14 row_mirror row_mask:0xf bank_mask:0xf bound_ctrl:1
	v_pk_fma_f32 v[2:3], v[110:111], v[14:15], v[18:19] op_sel_hi:[1,0,1]
	v_pk_fma_f32 v[4:5], v[112:113], v[14:15], v[20:21] op_sel_hi:[1,0,1]
	s_waitcnt lgkmcnt(0)
	v_pk_mul_f32 v[16:17], v[2:3], v[186:187] op_sel_hi:[0,1]
	v_pk_fma_f32 v[16:17], v[2:3], v[188:189], v[16:17] op_sel:[1,0,0] op_sel_hi:[1,1,1]
	v_pk_fma_f32 v[16:17], v[4:5], v[190:191], v[16:17] op_sel_hi:[0,1,1]
	v_pk_fma_f32 v[16:17], v[4:5], v[192:193], v[16:17] op_sel:[1,0,0] op_sel_hi:[1,1,1]
	v_fma_f32 v31, v210, v16, v17
	v_pk_mul_f32 v[18:19], v[202:203], v[206:207] op_sel:[0,1] op_sel_hi:[1,1]
	v_add_f32_dpp v16, v16, v16 quad_perm:[1,0,3,2] row_mask:0xf bank_mask:0xf bound_ctrl:1
	v_pk_mul_f32 v[20:21], v[204:205], v[206:207] op_sel:[0,1] op_sel_hi:[1,1]
	v_pk_fma_f32 v[18:19], v[2:3], v[194:195], v[18:19]
	v_add_f32_dpp v16, v16, v16 quad_perm:[2,3,0,1] row_mask:0xf bank_mask:0xf bound_ctrl:1
	v_pk_fma_f32 v[20:21], v[4:5], v[196:197], v[20:21]
	v_add_f32_dpp v33, v33, v33 row_ror:4 row_mask:0xf bank_mask:0xf bound_ctrl:1
	v_add_f32_dpp v16, v16, v16 row_half_mirror row_mask:0xf bank_mask:0xf bound_ctrl:1
	s_nop 0
	v_add_f32_dpp v33, v33, v33 row_ror:8 row_mask:0xf bank_mask:0xf bound_ctrl:1
	v_add_f32_dpp v16, v16, v16 row_mirror row_mask:0xf bank_mask:0xf bound_ctrl:1
	v_pk_fma_f32 v[2:3], v[198:199], v[16:17], v[18:19] op_sel_hi:[1,0,1]
	v_pk_fma_f32 v[4:5], v[200:201], v[16:17], v[20:21] op_sel_hi:[1,0,1]
	ds_write_b32 v56, v33 offset:1536
	v_cndmask_b32_e64 v32, v28, v29, s[98:99]
	v_cndmask_b32_e64 v33, v29, v28, s[98:99]
	v_cndmask_b32_e64 v23, v30, v31, s[98:99]
	v_cndmask_b32_e64 v57, v31, v30, s[98:99]
	v_add_f32_dpp v32, v33, v32 quad_perm:[1,0,3,2] row_mask:0xf bank_mask:0xf bound_ctrl:1
	s_nop 0
	v_add_f32_dpp v23, v57, v23 quad_perm:[1,0,3,2] row_mask:0xf bank_mask:0xf bound_ctrl:1
	v_cndmask_b32_e64 v57, v23, v32, s[100:101]
	v_cndmask_b32_e64 v33, v32, v23, s[100:101]
	s_nop 0
	v_add_f32_dpp v33, v57, v33 quad_perm:[2,3,0,1] row_mask:0xf bank_mask:0xf bound_ctrl:1
	s_nop 0
	s_nop 0
	v_add_f32_dpp v33, v33, v33 row_ror:4 row_mask:0xf bank_mask:0xf bound_ctrl:1
	s_nop 0
	s_nop 0
	v_add_f32_dpp v33, v33, v33 row_ror:8 row_mask:0xf bank_mask:0xf bound_ctrl:1
	ds_write_b32 v56, v33 offset:1792
	s_add_i32 s0, s0, 1
	s_cmpk_lg_i32 s0, 0x80
	s_waitcnt lgkmcnt(0)
	s_barrier
	s_cbranch_scc1 .LBB0_726
